# v15 with full-line residual epilogue requests: lanes fr/fr^8 trade 64-B halves through DPP so each x load/store covers 8 rows x 128 B
# speedup vs baseline: 1.0196x; 1.0047x over previous
.LBB0_293:
	s_ashr_i32 s3, s65, 31
	s_sub_i32 s4, s65, 64
	s_lshr_b32 s24, s65, 4
	s_cmp_gt_i32 s65, 63
	s_cselect_b32 s5, 0, s3
	s_cselect_b32 s4, s4, s65
	s_mulk_i32 s24, 0x4800
	s_waitcnt lgkmcnt(0)
	s_cselect_b32 s3, s15, s91
	s_cselect_b32 s28, s14, s90
	s_cselect_b32 s35, s14, s72
	s_cselect_b32 s42, s15, s73
	s_cselect_b32 s34, 0x12000, s24
	s_lshl_b64 s[4:5], s[4:5], 20
	s_add_u32 s28, s28, s4
	s_addc_u32 s29, s3, s5
	s_add_u32 s4, s35, s4
	s_addc_u32 s5, s42, s5
	s_ashr_i32 s35, s34, 31
	s_lshl_b32 s3, s85, 8
	s_or_b32 s3, s3, s1
	s_lshl_b64 s[34:35], s[34:35], 2
	s_add_u32 s34, s58, s34
	v_lshl_add_u32 v154, v67, 2, s3
	s_addc_u32 s35, s92, s35
	v_ashrrev_i32_e32 v155, 31, v154
	v_lshl_add_u64 v[156:157], v[154:155], 2, s[34:35]
	global_load_dwordx4 v[132:135], v[156:157], off
	global_load_dwordx4 v[136:139], v[156:157], off offset:64
	global_load_dwordx4 v[140:143], v[156:157], off offset:512
	global_load_dwordx4 v[168:171], v[156:157], off offset:576
	v_add_u32_e32 v163, s0, v164
	v_lshlrev_b32_e32 v163, 12, v163
	v_lshl_add_u32 v162, v154, 2, v163
	s_mov_b32 s3, 0xffff8040
	s_mov_b32 s24, 0x8000
	v_mov_b32_e32 v167, v162
	v_cmp_lt_u32_e32 vcc, 7, v164
	v_mov_b32_e32 v243, s3
	v_cndmask_b32_e32 v243, 0, v243, vcc
	v_mov_b32_e32 v163, s24
	v_cndmask_b32_e64 v163, v163, 64, vcc
	v_add_u32_e32 v163, v162, v163
	v_add_u32_e32 v162, v162, v243
	s_andn2_b64 vcc, exec, s[30:31]
	s_cbranch_vccz .Lepi_r_split
	global_load_dwordx4 v[150:153], v162, s[28:29]
	global_load_dwordx4 v[154:157], v163, s[28:29]
	global_load_dwordx4 v[158:161], v162, s[28:29] offset:512
	global_load_dwordx4 v[244:247], v163, s[28:29] offset:512
	s_add_u32 s28, s28, 0x10000
	s_addc_u32 s29, s29, 0
	global_load_dwordx4 v[248:251], v162, s[28:29]
	global_load_dwordx4 v[252:255], v163, s[28:29]
	global_load_dwordx4 v[172:175], v162, s[28:29] offset:512
	global_load_dwordx4 v[176:179], v163, s[28:29] offset:512
	s_add_u32 s28, s28, 0x10000
	s_addc_u32 s29, s29, 0
	global_load_dwordx4 v[190:193], v162, s[28:29]
	global_load_dwordx4 v[194:197], v163, s[28:29]
	global_load_dwordx4 v[198:201], v162, s[28:29] offset:512
	global_load_dwordx4 v[202:205], v163, s[28:29] offset:512
	s_add_u32 s28, s28, 0x10000
	s_addc_u32 s29, s29, 0
	global_load_dwordx4 v[206:209], v162, s[28:29]
	global_load_dwordx4 v[210:213], v163, s[28:29]
	global_load_dwordx4 v[214:217], v162, s[28:29] offset:512
	global_load_dwordx4 v[228:231], v163, s[28:29] offset:512
	s_waitcnt vmcnt(16)
	v_mul_f32_e32 v132, s88, v132
	v_mul_f32_e32 v133, s88, v133
	v_mul_f32_e32 v134, s88, v134
	v_mul_f32_e32 v135, s88, v135
	v_mul_f32_e32 v136, s88, v136
	v_mul_f32_e32 v137, s88, v137
	v_mul_f32_e32 v138, s88, v138
	v_mul_f32_e32 v139, s88, v139
	v_mul_f32_e32 v140, s88, v140
	v_mul_f32_e32 v141, s88, v141
	v_mul_f32_e32 v142, s88, v142
	v_mul_f32_e32 v143, s88, v143
	v_mul_f32_e32 v168, s88, v168
	v_mul_f32_e32 v169, s88, v169
	v_mul_f32_e32 v170, s88, v170
	v_mul_f32_e32 v171, s88, v171
	v_cmp_gt_u32_e32 vcc, 8, v164
	v_cndmask_b32_e32 v132, v136, v132, vcc
	v_cndmask_b32_e32 v133, v137, v133, vcc
	v_cndmask_b32_e32 v134, v138, v134, vcc
	v_cndmask_b32_e32 v135, v139, v135, vcc
	v_cndmask_b32_e32 v140, v168, v140, vcc
	v_cndmask_b32_e32 v141, v169, v141, vcc
	v_cndmask_b32_e32 v142, v170, v142, vcc
	v_cndmask_b32_e32 v143, v171, v143, vcc
	v_cndmask_b32_dpp v232, v124, v128, vcc row_ror:8 row_mask:0xf bank_mask:0xf
	v_cndmask_b32_dpp v233, v125, v129, vcc row_ror:8 row_mask:0xf bank_mask:0xf
	v_cndmask_b32_dpp v234, v126, v130, vcc row_ror:8 row_mask:0xf bank_mask:0xf
	v_cndmask_b32_dpp v235, v127, v131, vcc row_ror:8 row_mask:0xf bank_mask:0xf
	s_not_b64 vcc, vcc
	v_cndmask_b32_dpp v124, v128, v124, vcc row_ror:8 row_mask:0xf bank_mask:0xf
	v_cndmask_b32_dpp v125, v129, v125, vcc row_ror:8 row_mask:0xf bank_mask:0xf
	v_cndmask_b32_dpp v126, v130, v126, vcc row_ror:8 row_mask:0xf bank_mask:0xf
	v_cndmask_b32_dpp v127, v131, v127, vcc row_ror:8 row_mask:0xf bank_mask:0xf
	s_not_b64 vcc, vcc
	s_waitcnt vmcnt(14)
	v_pk_fma_f32 v[128:129], v[232:233], v[132:133], v[150:151]
	v_pk_fma_f32 v[130:131], v[234:235], v[134:135], v[152:153]
	v_pk_fma_f32 v[124:125], v[124:125], v[132:133], v[154:155]
	v_pk_fma_f32 v[126:127], v[126:127], v[134:135], v[156:157]
	s_add_u32 s28, s28, 0x50000
	s_addc_u32 s29, s29, 0
	global_load_dwordx4 v[150:153], v162, s[28:29]
	global_load_dwordx4 v[154:157], v163, s[28:29]
	v_cndmask_b32_dpp v232, v116, v120, vcc row_ror:8 row_mask:0xf bank_mask:0xf
	v_cndmask_b32_dpp v233, v117, v121, vcc row_ror:8 row_mask:0xf bank_mask:0xf
	v_cndmask_b32_dpp v234, v118, v122, vcc row_ror:8 row_mask:0xf bank_mask:0xf
	v_cndmask_b32_dpp v235, v119, v123, vcc row_ror:8 row_mask:0xf bank_mask:0xf
	s_not_b64 vcc, vcc
	v_cndmask_b32_dpp v116, v120, v116, vcc row_ror:8 row_mask:0xf bank_mask:0xf
	v_cndmask_b32_dpp v117, v121, v117, vcc row_ror:8 row_mask:0xf bank_mask:0xf
	v_cndmask_b32_dpp v118, v122, v118, vcc row_ror:8 row_mask:0xf bank_mask:0xf
	v_cndmask_b32_dpp v119, v123, v119, vcc row_ror:8 row_mask:0xf bank_mask:0xf
	s_not_b64 vcc, vcc
	s_waitcnt vmcnt(14)
	v_pk_fma_f32 v[120:121], v[232:233], v[140:141], v[158:159]
	v_pk_fma_f32 v[122:123], v[234:235], v[142:143], v[160:161]
	v_pk_fma_f32 v[116:117], v[116:117], v[140:141], v[244:245]
	v_pk_fma_f32 v[118:119], v[118:119], v[142:143], v[246:247]
	global_load_dwordx4 v[158:161], v162, s[28:29] offset:512
	global_load_dwordx4 v[244:247], v163, s[28:29] offset:512
	v_cndmask_b32_dpp v232, v108, v112, vcc row_ror:8 row_mask:0xf bank_mask:0xf
	v_cndmask_b32_dpp v233, v109, v113, vcc row_ror:8 row_mask:0xf bank_mask:0xf
	v_cndmask_b32_dpp v234, v110, v114, vcc row_ror:8 row_mask:0xf bank_mask:0xf
	v_cndmask_b32_dpp v235, v111, v115, vcc row_ror:8 row_mask:0xf bank_mask:0xf
	s_not_b64 vcc, vcc
	v_cndmask_b32_dpp v108, v112, v108, vcc row_ror:8 row_mask:0xf bank_mask:0xf
	v_cndmask_b32_dpp v109, v113, v109, vcc row_ror:8 row_mask:0xf bank_mask:0xf
	v_cndmask_b32_dpp v110, v114, v110, vcc row_ror:8 row_mask:0xf bank_mask:0xf
	v_cndmask_b32_dpp v111, v115, v111, vcc row_ror:8 row_mask:0xf bank_mask:0xf
	s_not_b64 vcc, vcc
	s_waitcnt vmcnt(14)
	v_pk_fma_f32 v[112:113], v[232:233], v[132:133], v[248:249]
	v_pk_fma_f32 v[114:115], v[234:235], v[134:135], v[250:251]
	v_pk_fma_f32 v[108:109], v[108:109], v[132:133], v[252:253]
	v_pk_fma_f32 v[110:111], v[110:111], v[134:135], v[254:255]
	s_add_u32 s28, s28, 0x10000
	s_addc_u32 s29, s29, 0
	global_load_dwordx4 v[248:251], v162, s[28:29]
	global_load_dwordx4 v[252:255], v163, s[28:29]
	v_cndmask_b32_dpp v232, v100, v104, vcc row_ror:8 row_mask:0xf bank_mask:0xf
	v_cndmask_b32_dpp v233, v101, v105, vcc row_ror:8 row_mask:0xf bank_mask:0xf
	v_cndmask_b32_dpp v234, v102, v106, vcc row_ror:8 row_mask:0xf bank_mask:0xf
	v_cndmask_b32_dpp v235, v103, v107, vcc row_ror:8 row_mask:0xf bank_mask:0xf
	s_not_b64 vcc, vcc
	v_cndmask_b32_dpp v100, v104, v100, vcc row_ror:8 row_mask:0xf bank_mask:0xf
	v_cndmask_b32_dpp v101, v105, v101, vcc row_ror:8 row_mask:0xf bank_mask:0xf
	v_cndmask_b32_dpp v102, v106, v102, vcc row_ror:8 row_mask:0xf bank_mask:0xf
	v_cndmask_b32_dpp v103, v107, v103, vcc row_ror:8 row_mask:0xf bank_mask:0xf
	s_not_b64 vcc, vcc
	s_waitcnt vmcnt(14)
	v_pk_fma_f32 v[104:105], v[232:233], v[140:141], v[172:173]
	v_pk_fma_f32 v[106:107], v[234:235], v[142:143], v[174:175]
	v_pk_fma_f32 v[100:101], v[100:101], v[140:141], v[176:177]
	v_pk_fma_f32 v[102:103], v[102:103], v[142:143], v[178:179]
	global_load_dwordx4 v[172:175], v162, s[28:29] offset:512
	global_load_dwordx4 v[176:179], v163, s[28:29] offset:512
	v_cndmask_b32_dpp v232, v92, v96, vcc row_ror:8 row_mask:0xf bank_mask:0xf
	v_cndmask_b32_dpp v233, v93, v97, vcc row_ror:8 row_mask:0xf bank_mask:0xf
	v_cndmask_b32_dpp v234, v94, v98, vcc row_ror:8 row_mask:0xf bank_mask:0xf
	v_cndmask_b32_dpp v235, v95, v99, vcc row_ror:8 row_mask:0xf bank_mask:0xf
	s_not_b64 vcc, vcc
	v_cndmask_b32_dpp v92, v96, v92, vcc row_ror:8 row_mask:0xf bank_mask:0xf
	v_cndmask_b32_dpp v93, v97, v93, vcc row_ror:8 row_mask:0xf bank_mask:0xf
	v_cndmask_b32_dpp v94, v98, v94, vcc row_ror:8 row_mask:0xf bank_mask:0xf
	v_cndmask_b32_dpp v95, v99, v95, vcc row_ror:8 row_mask:0xf bank_mask:0xf
	s_not_b64 vcc, vcc
	s_waitcnt vmcnt(14)
	v_pk_fma_f32 v[96:97], v[232:233], v[132:133], v[190:191]
	v_pk_fma_f32 v[98:99], v[234:235], v[134:135], v[192:193]
	v_pk_fma_f32 v[92:93], v[92:93], v[132:133], v[194:195]
	v_pk_fma_f32 v[94:95], v[94:95], v[134:135], v[196:197]
	s_add_u32 s28, s28, 0x10000
	s_addc_u32 s29, s29, 0
	global_load_dwordx4 v[190:193], v162, s[28:29]
	global_load_dwordx4 v[194:197], v163, s[28:29]
	v_cndmask_b32_dpp v232, v84, v88, vcc row_ror:8 row_mask:0xf bank_mask:0xf
	v_cndmask_b32_dpp v233, v85, v89, vcc row_ror:8 row_mask:0xf bank_mask:0xf
	v_cndmask_b32_dpp v234, v86, v90, vcc row_ror:8 row_mask:0xf bank_mask:0xf
	v_cndmask_b32_dpp v235, v87, v91, vcc row_ror:8 row_mask:0xf bank_mask:0xf
	s_not_b64 vcc, vcc
	v_cndmask_b32_dpp v84, v88, v84, vcc row_ror:8 row_mask:0xf bank_mask:0xf
	v_cndmask_b32_dpp v85, v89, v85, vcc row_ror:8 row_mask:0xf bank_mask:0xf
	v_cndmask_b32_dpp v86, v90, v86, vcc row_ror:8 row_mask:0xf bank_mask:0xf
	v_cndmask_b32_dpp v87, v91, v87, vcc row_ror:8 row_mask:0xf bank_mask:0xf
	s_not_b64 vcc, vcc
	s_waitcnt vmcnt(14)
	v_pk_fma_f32 v[88:89], v[232:233], v[140:141], v[198:199]
	v_pk_fma_f32 v[90:91], v[234:235], v[142:143], v[200:201]
	v_pk_fma_f32 v[84:85], v[84:85], v[140:141], v[202:203]
	v_pk_fma_f32 v[86:87], v[86:87], v[142:143], v[204:205]
	global_load_dwordx4 v[198:201], v162, s[28:29] offset:512
	global_load_dwordx4 v[202:205], v163, s[28:29] offset:512
	v_cndmask_b32_dpp v232, v76, v80, vcc row_ror:8 row_mask:0xf bank_mask:0xf
	v_cndmask_b32_dpp v233, v77, v81, vcc row_ror:8 row_mask:0xf bank_mask:0xf
	v_cndmask_b32_dpp v234, v78, v82, vcc row_ror:8 row_mask:0xf bank_mask:0xf
	v_cndmask_b32_dpp v235, v79, v83, vcc row_ror:8 row_mask:0xf bank_mask:0xf
	s_not_b64 vcc, vcc
	v_cndmask_b32_dpp v76, v80, v76, vcc row_ror:8 row_mask:0xf bank_mask:0xf
	v_cndmask_b32_dpp v77, v81, v77, vcc row_ror:8 row_mask:0xf bank_mask:0xf
	v_cndmask_b32_dpp v78, v82, v78, vcc row_ror:8 row_mask:0xf bank_mask:0xf
	v_cndmask_b32_dpp v79, v83, v79, vcc row_ror:8 row_mask:0xf bank_mask:0xf
	s_not_b64 vcc, vcc
	s_waitcnt vmcnt(14)
	v_pk_fma_f32 v[80:81], v[232:233], v[132:133], v[206:207]
	v_pk_fma_f32 v[82:83], v[234:235], v[134:135], v[208:209]
	v_pk_fma_f32 v[76:77], v[76:77], v[132:133], v[210:211]
	v_pk_fma_f32 v[78:79], v[78:79], v[134:135], v[212:213]
	s_add_u32 s28, s28, 0x10000
	s_addc_u32 s29, s29, 0
	global_load_dwordx4 v[206:209], v162, s[28:29]
	global_load_dwordx4 v[210:213], v163, s[28:29]
	v_cndmask_b32_dpp v232, v68, v72, vcc row_ror:8 row_mask:0xf bank_mask:0xf
	v_cndmask_b32_dpp v233, v69, v73, vcc row_ror:8 row_mask:0xf bank_mask:0xf
	v_cndmask_b32_dpp v234, v70, v74, vcc row_ror:8 row_mask:0xf bank_mask:0xf
	v_cndmask_b32_dpp v235, v71, v75, vcc row_ror:8 row_mask:0xf bank_mask:0xf
	s_not_b64 vcc, vcc
	v_cndmask_b32_dpp v68, v72, v68, vcc row_ror:8 row_mask:0xf bank_mask:0xf
	v_cndmask_b32_dpp v69, v73, v69, vcc row_ror:8 row_mask:0xf bank_mask:0xf
	v_cndmask_b32_dpp v70, v74, v70, vcc row_ror:8 row_mask:0xf bank_mask:0xf
	v_cndmask_b32_dpp v71, v75, v71, vcc row_ror:8 row_mask:0xf bank_mask:0xf
	s_not_b64 vcc, vcc
	s_waitcnt vmcnt(14)
	v_pk_fma_f32 v[72:73], v[232:233], v[140:141], v[214:215]
	v_pk_fma_f32 v[74:75], v[234:235], v[142:143], v[216:217]
	v_pk_fma_f32 v[68:69], v[68:69], v[140:141], v[228:229]
	v_pk_fma_f32 v[70:71], v[70:71], v[142:143], v[230:231]
	global_load_dwordx4 v[214:217], v162, s[28:29] offset:512
	global_load_dwordx4 v[228:231], v163, s[28:29] offset:512
	v_cndmask_b32_dpp v232, v58, v62, vcc row_ror:8 row_mask:0xf bank_mask:0xf
	v_cndmask_b32_dpp v233, v59, v63, vcc row_ror:8 row_mask:0xf bank_mask:0xf
	v_cndmask_b32_dpp v234, v60, v64, vcc row_ror:8 row_mask:0xf bank_mask:0xf
	v_cndmask_b32_dpp v235, v61, v65, vcc row_ror:8 row_mask:0xf bank_mask:0xf
	s_not_b64 vcc, vcc
	v_cndmask_b32_dpp v58, v62, v58, vcc row_ror:8 row_mask:0xf bank_mask:0xf
	v_cndmask_b32_dpp v59, v63, v59, vcc row_ror:8 row_mask:0xf bank_mask:0xf
	v_cndmask_b32_dpp v60, v64, v60, vcc row_ror:8 row_mask:0xf bank_mask:0xf
	v_cndmask_b32_dpp v61, v65, v61, vcc row_ror:8 row_mask:0xf bank_mask:0xf
	s_not_b64 vcc, vcc
	s_waitcnt vmcnt(14)
	v_pk_fma_f32 v[62:63], v[232:233], v[132:133], v[150:151]
	v_pk_fma_f32 v[64:65], v[234:235], v[134:135], v[152:153]
	v_pk_fma_f32 v[58:59], v[58:59], v[132:133], v[154:155]
	v_pk_fma_f32 v[60:61], v[60:61], v[134:135], v[156:157]
	v_cndmask_b32_dpp v232, v50, v54, vcc row_ror:8 row_mask:0xf bank_mask:0xf
	v_cndmask_b32_dpp v233, v51, v55, vcc row_ror:8 row_mask:0xf bank_mask:0xf
	v_cndmask_b32_dpp v234, v52, v56, vcc row_ror:8 row_mask:0xf bank_mask:0xf
	v_cndmask_b32_dpp v235, v53, v57, vcc row_ror:8 row_mask:0xf bank_mask:0xf
	s_not_b64 vcc, vcc
	v_cndmask_b32_dpp v50, v54, v50, vcc row_ror:8 row_mask:0xf bank_mask:0xf
	v_cndmask_b32_dpp v51, v55, v51, vcc row_ror:8 row_mask:0xf bank_mask:0xf
	v_cndmask_b32_dpp v52, v56, v52, vcc row_ror:8 row_mask:0xf bank_mask:0xf
	v_cndmask_b32_dpp v53, v57, v53, vcc row_ror:8 row_mask:0xf bank_mask:0xf
	s_not_b64 vcc, vcc
	s_waitcnt vmcnt(12)
	v_pk_fma_f32 v[54:55], v[232:233], v[140:141], v[158:159]
	v_pk_fma_f32 v[56:57], v[234:235], v[142:143], v[160:161]
	v_pk_fma_f32 v[50:51], v[50:51], v[140:141], v[244:245]
	v_pk_fma_f32 v[52:53], v[52:53], v[142:143], v[246:247]
	v_cndmask_b32_dpp v232, v42, v46, vcc row_ror:8 row_mask:0xf bank_mask:0xf
	v_cndmask_b32_dpp v233, v43, v47, vcc row_ror:8 row_mask:0xf bank_mask:0xf
	v_cndmask_b32_dpp v234, v44, v48, vcc row_ror:8 row_mask:0xf bank_mask:0xf
	v_cndmask_b32_dpp v235, v45, v49, vcc row_ror:8 row_mask:0xf bank_mask:0xf
	s_not_b64 vcc, vcc
	v_cndmask_b32_dpp v42, v46, v42, vcc row_ror:8 row_mask:0xf bank_mask:0xf
	v_cndmask_b32_dpp v43, v47, v43, vcc row_ror:8 row_mask:0xf bank_mask:0xf
	v_cndmask_b32_dpp v44, v48, v44, vcc row_ror:8 row_mask:0xf bank_mask:0xf
	v_cndmask_b32_dpp v45, v49, v45, vcc row_ror:8 row_mask:0xf bank_mask:0xf
	s_not_b64 vcc, vcc
	s_waitcnt vmcnt(10)
	v_pk_fma_f32 v[46:47], v[232:233], v[132:133], v[248:249]
	v_pk_fma_f32 v[48:49], v[234:235], v[134:135], v[250:251]
	v_pk_fma_f32 v[42:43], v[42:43], v[132:133], v[252:253]
	v_pk_fma_f32 v[44:45], v[44:45], v[134:135], v[254:255]
	v_cndmask_b32_dpp v232, v34, v38, vcc row_ror:8 row_mask:0xf bank_mask:0xf
	v_cndmask_b32_dpp v233, v35, v39, vcc row_ror:8 row_mask:0xf bank_mask:0xf
	v_cndmask_b32_dpp v234, v36, v40, vcc row_ror:8 row_mask:0xf bank_mask:0xf
	v_cndmask_b32_dpp v235, v37, v41, vcc row_ror:8 row_mask:0xf bank_mask:0xf
	s_not_b64 vcc, vcc
	v_cndmask_b32_dpp v34, v38, v34, vcc row_ror:8 row_mask:0xf bank_mask:0xf
	v_cndmask_b32_dpp v35, v39, v35, vcc row_ror:8 row_mask:0xf bank_mask:0xf
	v_cndmask_b32_dpp v36, v40, v36, vcc row_ror:8 row_mask:0xf bank_mask:0xf
	v_cndmask_b32_dpp v37, v41, v37, vcc row_ror:8 row_mask:0xf bank_mask:0xf
	s_not_b64 vcc, vcc
	s_waitcnt vmcnt(8)
	v_pk_fma_f32 v[38:39], v[232:233], v[140:141], v[172:173]
	v_pk_fma_f32 v[40:41], v[234:235], v[142:143], v[174:175]
	v_pk_fma_f32 v[34:35], v[34:35], v[140:141], v[176:177]
	v_pk_fma_f32 v[36:37], v[36:37], v[142:143], v[178:179]
	v_cndmask_b32_dpp v232, v26, v30, vcc row_ror:8 row_mask:0xf bank_mask:0xf
	v_cndmask_b32_dpp v233, v27, v31, vcc row_ror:8 row_mask:0xf bank_mask:0xf
	v_cndmask_b32_dpp v234, v28, v32, vcc row_ror:8 row_mask:0xf bank_mask:0xf
	v_cndmask_b32_dpp v235, v29, v33, vcc row_ror:8 row_mask:0xf bank_mask:0xf
	s_not_b64 vcc, vcc
	v_cndmask_b32_dpp v26, v30, v26, vcc row_ror:8 row_mask:0xf bank_mask:0xf
	v_cndmask_b32_dpp v27, v31, v27, vcc row_ror:8 row_mask:0xf bank_mask:0xf
	v_cndmask_b32_dpp v28, v32, v28, vcc row_ror:8 row_mask:0xf bank_mask:0xf
	v_cndmask_b32_dpp v29, v33, v29, vcc row_ror:8 row_mask:0xf bank_mask:0xf
	s_not_b64 vcc, vcc
	s_waitcnt vmcnt(6)
	v_pk_fma_f32 v[30:31], v[232:233], v[132:133], v[190:191]
	v_pk_fma_f32 v[32:33], v[234:235], v[134:135], v[192:193]
	v_pk_fma_f32 v[26:27], v[26:27], v[132:133], v[194:195]
	v_pk_fma_f32 v[28:29], v[28:29], v[134:135], v[196:197]
	v_cndmask_b32_dpp v232, v18, v22, vcc row_ror:8 row_mask:0xf bank_mask:0xf
	v_cndmask_b32_dpp v233, v19, v23, vcc row_ror:8 row_mask:0xf bank_mask:0xf
	v_cndmask_b32_dpp v234, v20, v24, vcc row_ror:8 row_mask:0xf bank_mask:0xf
	v_cndmask_b32_dpp v235, v21, v25, vcc row_ror:8 row_mask:0xf bank_mask:0xf
	s_not_b64 vcc, vcc
	v_cndmask_b32_dpp v18, v22, v18, vcc row_ror:8 row_mask:0xf bank_mask:0xf
	v_cndmask_b32_dpp v19, v23, v19, vcc row_ror:8 row_mask:0xf bank_mask:0xf
	v_cndmask_b32_dpp v20, v24, v20, vcc row_ror:8 row_mask:0xf bank_mask:0xf
	v_cndmask_b32_dpp v21, v25, v21, vcc row_ror:8 row_mask:0xf bank_mask:0xf
	s_not_b64 vcc, vcc
	s_waitcnt vmcnt(4)
	v_pk_fma_f32 v[22:23], v[232:233], v[140:141], v[198:199]
	v_pk_fma_f32 v[24:25], v[234:235], v[142:143], v[200:201]
	v_pk_fma_f32 v[18:19], v[18:19], v[140:141], v[202:203]
	v_pk_fma_f32 v[20:21], v[20:21], v[142:143], v[204:205]
	v_cndmask_b32_dpp v232, v10, v14, vcc row_ror:8 row_mask:0xf bank_mask:0xf
	v_cndmask_b32_dpp v233, v11, v15, vcc row_ror:8 row_mask:0xf bank_mask:0xf
	v_cndmask_b32_dpp v234, v12, v16, vcc row_ror:8 row_mask:0xf bank_mask:0xf
	v_cndmask_b32_dpp v235, v13, v17, vcc row_ror:8 row_mask:0xf bank_mask:0xf
	s_not_b64 vcc, vcc
	v_cndmask_b32_dpp v10, v14, v10, vcc row_ror:8 row_mask:0xf bank_mask:0xf
	v_cndmask_b32_dpp v11, v15, v11, vcc row_ror:8 row_mask:0xf bank_mask:0xf
	v_cndmask_b32_dpp v12, v16, v12, vcc row_ror:8 row_mask:0xf bank_mask:0xf
	v_cndmask_b32_dpp v13, v17, v13, vcc row_ror:8 row_mask:0xf bank_mask:0xf
	s_not_b64 vcc, vcc
	s_waitcnt vmcnt(2)
	v_pk_fma_f32 v[14:15], v[232:233], v[132:133], v[206:207]
	v_pk_fma_f32 v[16:17], v[234:235], v[134:135], v[208:209]
	v_pk_fma_f32 v[10:11], v[10:11], v[132:133], v[210:211]
	v_pk_fma_f32 v[12:13], v[12:13], v[134:135], v[212:213]
	v_cndmask_b32_dpp v232, v2, v6, vcc row_ror:8 row_mask:0xf bank_mask:0xf
	v_cndmask_b32_dpp v233, v3, v7, vcc row_ror:8 row_mask:0xf bank_mask:0xf
	v_cndmask_b32_dpp v234, v4, v8, vcc row_ror:8 row_mask:0xf bank_mask:0xf
	v_cndmask_b32_dpp v235, v5, v9, vcc row_ror:8 row_mask:0xf bank_mask:0xf
	s_not_b64 vcc, vcc
	v_cndmask_b32_dpp v2, v6, v2, vcc row_ror:8 row_mask:0xf bank_mask:0xf
	v_cndmask_b32_dpp v3, v7, v3, vcc row_ror:8 row_mask:0xf bank_mask:0xf
	v_cndmask_b32_dpp v4, v8, v4, vcc row_ror:8 row_mask:0xf bank_mask:0xf
	v_cndmask_b32_dpp v5, v9, v5, vcc row_ror:8 row_mask:0xf bank_mask:0xf
	s_not_b64 vcc, vcc
	s_waitcnt vmcnt(0)
	v_pk_fma_f32 v[6:7], v[232:233], v[140:141], v[214:215]
	v_pk_fma_f32 v[8:9], v[234:235], v[142:143], v[216:217]
	v_pk_fma_f32 v[2:3], v[2:3], v[140:141], v[228:229]
	v_pk_fma_f32 v[4:5], v[4:5], v[142:143], v[230:231]
	global_store_dwordx4 v162, v[128:131], s[4:5]
	global_store_dwordx4 v163, v[124:127], s[4:5]
	global_store_dwordx4 v162, v[120:123], s[4:5] offset:512
	global_store_dwordx4 v163, v[116:119], s[4:5] offset:512
	s_add_u32 s4, s4, 0x10000
	s_addc_u32 s5, s5, 0
	global_store_dwordx4 v162, v[112:115], s[4:5]
	global_store_dwordx4 v163, v[108:111], s[4:5]
	global_store_dwordx4 v162, v[104:107], s[4:5] offset:512
	global_store_dwordx4 v163, v[100:103], s[4:5] offset:512
	s_add_u32 s4, s4, 0x10000
	s_addc_u32 s5, s5, 0
	global_store_dwordx4 v162, v[96:99], s[4:5]
	global_store_dwordx4 v163, v[92:95], s[4:5]
	global_store_dwordx4 v162, v[88:91], s[4:5] offset:512
	global_store_dwordx4 v163, v[84:87], s[4:5] offset:512
	s_add_u32 s4, s4, 0x10000
	s_addc_u32 s5, s5, 0
	global_store_dwordx4 v162, v[80:83], s[4:5]
	global_store_dwordx4 v163, v[76:79], s[4:5]
	global_store_dwordx4 v162, v[72:75], s[4:5] offset:512
	global_store_dwordx4 v163, v[68:71], s[4:5] offset:512
	s_add_u32 s4, s4, 0x50000
	s_addc_u32 s5, s5, 0
	global_store_dwordx4 v162, v[62:65], s[4:5]
	global_store_dwordx4 v163, v[58:61], s[4:5]
	global_store_dwordx4 v162, v[54:57], s[4:5] offset:512
	global_store_dwordx4 v163, v[50:53], s[4:5] offset:512
	s_add_u32 s4, s4, 0x10000
	s_addc_u32 s5, s5, 0
	global_store_dwordx4 v162, v[46:49], s[4:5]
	global_store_dwordx4 v163, v[42:45], s[4:5]
	global_store_dwordx4 v162, v[38:41], s[4:5] offset:512
	global_store_dwordx4 v163, v[34:37], s[4:5] offset:512
	s_add_u32 s4, s4, 0x10000
	s_addc_u32 s5, s5, 0
	global_store_dwordx4 v162, v[30:33], s[4:5]
	global_store_dwordx4 v163, v[26:29], s[4:5]
	global_store_dwordx4 v162, v[22:25], s[4:5] offset:512
	global_store_dwordx4 v163, v[18:21], s[4:5] offset:512
	s_add_u32 s4, s4, 0x10000
	s_addc_u32 s5, s5, 0
	global_store_dwordx4 v162, v[14:17], s[4:5]
	global_store_dwordx4 v163, v[10:13], s[4:5]
	global_store_dwordx4 v162, v[6:9], s[4:5] offset:512
	global_store_dwordx4 v163, v[2:5], s[4:5] offset:512
	s_branch .Lepi_r_done
.Lepi_r_split:
	s_lshl_b32 s3, s65, 8
	s_ashr_i32 s85, s84, 31
	s_add_i32 s30, s3, 0xffffc000
	s_ashr_i32 s31, s30, 31
	s_lshl_b64 s[34:35], s[84:85], 22
	s_add_u32 s3, s93, s34
	s_addc_u32 s24, s53, s35
	s_lshl_b64 s[30:31], s[30:31], 12
	s_add_u32 s30, s3, s30
	s_addc_u32 s31, s24, s31
	s_waitcnt vmcnt(0)
	v_mul_f32_e32 v132, s88, v132
	v_mul_f32_e32 v133, s88, v133
	v_mul_f32_e32 v134, s88, v134
	v_mul_f32_e32 v135, s88, v135
	v_mul_f32_e32 v136, s88, v136
	v_mul_f32_e32 v137, s88, v137
	v_mul_f32_e32 v138, s88, v138
	v_mul_f32_e32 v139, s88, v139
	v_mul_f32_e32 v140, s88, v140
	v_mul_f32_e32 v141, s88, v141
	v_mul_f32_e32 v142, s88, v142
	v_mul_f32_e32 v143, s88, v143
	v_mul_f32_e32 v168, s88, v168
	v_mul_f32_e32 v169, s88, v169
	v_mul_f32_e32 v170, s88, v170
	v_mul_f32_e32 v171, s88, v171
	v_pk_mul_f32 v[150:151], v[132:133], v[128:129]
	v_pk_mul_f32 v[152:153], v[134:135], v[130:131]
	global_store_dwordx4 v167, v[150:153], s[30:31]
	v_pk_mul_f32 v[154:155], v[136:137], v[124:125]
	v_pk_mul_f32 v[156:157], v[138:139], v[126:127]
	global_store_dwordx4 v167, v[154:157], s[30:31] offset:64
	v_pk_mul_f32 v[158:159], v[140:141], v[120:121]
	v_pk_mul_f32 v[160:161], v[142:143], v[122:123]
	global_store_dwordx4 v167, v[158:161], s[30:31] offset:512
	v_pk_mul_f32 v[244:245], v[168:169], v[116:117]
	v_pk_mul_f32 v[246:247], v[170:171], v[118:119]
	global_store_dwordx4 v167, v[244:247], s[30:31] offset:576
	s_add_u32 s30, s30, 0x10000
	s_addc_u32 s31, s31, 0
	v_pk_mul_f32 v[248:249], v[132:133], v[112:113]
	v_pk_mul_f32 v[250:251], v[134:135], v[114:115]
	global_store_dwordx4 v167, v[248:251], s[30:31]
	v_pk_mul_f32 v[252:253], v[136:137], v[108:109]
	v_pk_mul_f32 v[254:255], v[138:139], v[110:111]
	global_store_dwordx4 v167, v[252:255], s[30:31] offset:64
	v_pk_mul_f32 v[150:151], v[140:141], v[104:105]
	v_pk_mul_f32 v[152:153], v[142:143], v[106:107]
	global_store_dwordx4 v167, v[150:153], s[30:31] offset:512
	v_pk_mul_f32 v[154:155], v[168:169], v[100:101]
	v_pk_mul_f32 v[156:157], v[170:171], v[102:103]
	global_store_dwordx4 v167, v[154:157], s[30:31] offset:576
	s_add_u32 s30, s30, 0x10000
	s_addc_u32 s31, s31, 0
	v_pk_mul_f32 v[158:159], v[132:133], v[96:97]
	v_pk_mul_f32 v[160:161], v[134:135], v[98:99]
	global_store_dwordx4 v167, v[158:161], s[30:31]
	v_pk_mul_f32 v[244:245], v[136:137], v[92:93]
	v_pk_mul_f32 v[246:247], v[138:139], v[94:95]
	global_store_dwordx4 v167, v[244:247], s[30:31] offset:64
	v_pk_mul_f32 v[248:249], v[140:141], v[88:89]
	v_pk_mul_f32 v[250:251], v[142:143], v[90:91]
	global_store_dwordx4 v167, v[248:251], s[30:31] offset:512
	v_pk_mul_f32 v[252:253], v[168:169], v[84:85]
	v_pk_mul_f32 v[254:255], v[170:171], v[86:87]
	global_store_dwordx4 v167, v[252:255], s[30:31] offset:576
	s_add_u32 s30, s30, 0x10000
	s_addc_u32 s31, s31, 0
	v_pk_mul_f32 v[150:151], v[132:133], v[80:81]
	v_pk_mul_f32 v[152:153], v[134:135], v[82:83]
	global_store_dwordx4 v167, v[150:153], s[30:31]
	v_pk_mul_f32 v[154:155], v[136:137], v[76:77]
	v_pk_mul_f32 v[156:157], v[138:139], v[78:79]
	global_store_dwordx4 v167, v[154:157], s[30:31] offset:64
	v_pk_mul_f32 v[158:159], v[140:141], v[72:73]
	v_pk_mul_f32 v[160:161], v[142:143], v[74:75]
	global_store_dwordx4 v167, v[158:161], s[30:31] offset:512
	v_pk_mul_f32 v[244:245], v[168:169], v[68:69]
	v_pk_mul_f32 v[246:247], v[170:171], v[70:71]
	global_store_dwordx4 v167, v[244:247], s[30:31] offset:576
	s_add_u32 s30, s30, 0x50000
	s_addc_u32 s31, s31, 0
	v_pk_mul_f32 v[248:249], v[132:133], v[62:63]
	v_pk_mul_f32 v[250:251], v[134:135], v[64:65]
	global_store_dwordx4 v167, v[248:251], s[30:31]
	v_pk_mul_f32 v[252:253], v[136:137], v[58:59]
	v_pk_mul_f32 v[254:255], v[138:139], v[60:61]
	global_store_dwordx4 v167, v[252:255], s[30:31] offset:64
	v_pk_mul_f32 v[150:151], v[140:141], v[54:55]
	v_pk_mul_f32 v[152:153], v[142:143], v[56:57]
	global_store_dwordx4 v167, v[150:153], s[30:31] offset:512
	v_pk_mul_f32 v[154:155], v[168:169], v[50:51]
	v_pk_mul_f32 v[156:157], v[170:171], v[52:53]
	global_store_dwordx4 v167, v[154:157], s[30:31] offset:576
	s_add_u32 s30, s30, 0x10000
	s_addc_u32 s31, s31, 0
	v_pk_mul_f32 v[158:159], v[132:133], v[46:47]
	v_pk_mul_f32 v[160:161], v[134:135], v[48:49]
	global_store_dwordx4 v167, v[158:161], s[30:31]
	v_pk_mul_f32 v[244:245], v[136:137], v[42:43]
	v_pk_mul_f32 v[246:247], v[138:139], v[44:45]
	global_store_dwordx4 v167, v[244:247], s[30:31] offset:64
	v_pk_mul_f32 v[248:249], v[140:141], v[38:39]
	v_pk_mul_f32 v[250:251], v[142:143], v[40:41]
	global_store_dwordx4 v167, v[248:251], s[30:31] offset:512
	v_pk_mul_f32 v[252:253], v[168:169], v[34:35]
	v_pk_mul_f32 v[254:255], v[170:171], v[36:37]
	global_store_dwordx4 v167, v[252:255], s[30:31] offset:576
	s_add_u32 s30, s30, 0x10000
	s_addc_u32 s31, s31, 0
	v_pk_mul_f32 v[150:151], v[132:133], v[30:31]
	v_pk_mul_f32 v[152:153], v[134:135], v[32:33]
	global_store_dwordx4 v167, v[150:153], s[30:31]
	v_pk_mul_f32 v[154:155], v[136:137], v[26:27]
	v_pk_mul_f32 v[156:157], v[138:139], v[28:29]
	global_store_dwordx4 v167, v[154:157], s[30:31] offset:64
	v_pk_mul_f32 v[158:159], v[140:141], v[22:23]
	v_pk_mul_f32 v[160:161], v[142:143], v[24:25]
	global_store_dwordx4 v167, v[158:161], s[30:31] offset:512
	v_pk_mul_f32 v[244:245], v[168:169], v[18:19]
	v_pk_mul_f32 v[246:247], v[170:171], v[20:21]
	global_store_dwordx4 v167, v[244:247], s[30:31] offset:576
	s_add_u32 s30, s30, 0x10000
	s_addc_u32 s31, s31, 0
	v_pk_mul_f32 v[248:249], v[132:133], v[14:15]
	v_pk_mul_f32 v[250:251], v[134:135], v[16:17]
	global_store_dwordx4 v167, v[248:251], s[30:31]
	v_pk_mul_f32 v[252:253], v[136:137], v[10:11]
	v_pk_mul_f32 v[254:255], v[138:139], v[12:13]
	global_store_dwordx4 v167, v[252:255], s[30:31] offset:64
	v_pk_mul_f32 v[150:151], v[140:141], v[6:7]
	v_pk_mul_f32 v[152:153], v[142:143], v[8:9]
	global_store_dwordx4 v167, v[150:153], s[30:31] offset:512
	v_pk_mul_f32 v[154:155], v[168:169], v[2:3]
	v_pk_mul_f32 v[156:157], v[170:171], v[4:5]
	global_store_dwordx4 v167, v[154:157], s[30:31] offset:576
